# final RMSNorm row loop: batch 16 partial + 4 X loads per row, hoist gain loads
# speedup vs baseline: 1.0014x; 1.0014x over previous
.LBB0_8:
	s_add_i32 s0, s96, -1
	s_mul_hi_i32 s2, s0, 0x4ec4ec4f
	s_lshr_b32 s3, s2, 31
	s_ashr_i32 s38, s2, 2
	v_writelane_b32 v255, s77, 43
	s_add_i32 s77, s38, s3
	s_mul_i32 s2, s77, 13
	s_sub_i32 s59, s0, s2
	s_mov_b32 s58, 0x800000
	s_mov_b64 s[2:3], -1
	s_mov_b64 s[12:13], 0
	s_cmp_lt_i32 s59, 6
	s_mov_b64 s[18:19], 0
	s_mov_b64 s[20:21], 0
	s_cbranch_scc1 .LBB0_265
	s_cmp_gt_i32 s59, 8
	s_cbranch_scc0 .LBB0_44
	s_cmp_gt_i32 s59, 10
	s_cbranch_scc0 .LBB0_221
	s_cmp_gt_i32 s59, 11
	s_mov_b64 s[20:21], -1
	s_cbranch_scc0 .LBB0_220
	s_cmp_eq_u32 s59, 12
	s_cbranch_scc0 .LBB0_219
	s_add_i32 s0, s96, 11
	s_cmp_gt_u32 s0, 24
	s_cbranch_scc0 .LBB0_18
	v_ashrrev_i32_e32 v0, 6, v152
	v_readlane_b32 s0, v255, 43
	s_mov_b64 s[2:3], s[74:75]
	s_nop 0
	v_lshl_add_u32 v0, s0, 2, v0
	s_movk_i32 s0, 0x4000
	v_cmp_gt_i32_e32 vcc, s0, v0
	s_and_saveexec_b64 s[6:7], vcc
	v_readlane_b32 s22, v255, 8
	v_readlane_b32 s24, v255, 12
	v_readlane_b32 s20, v255, 6
	v_readlane_b32 s23, v255, 9
	v_readlane_b32 s25, v255, 13
	s_mov_b32 s26, 0x800000
	s_movk_i32 s27, 0x3fff
	v_readlane_b32 s21, v255, 7
	s_cbranch_execz .LBB0_17
	v_ashrrev_i32_e32 v1, 31, v0
	v_lshl_add_u64 v[2:3], v[0:1], 2, s[2:3]
	s_mov_b64 s[2:3], 0x122d0000
	v_lshl_add_u64 v[2:3], v[2:3], 0, s[2:3]
	v_lshlrev_b64 v[4:5], 12, v[0:1]
	v_readlane_b32 s2, v255, 10
	v_lshlrev_b32_e32 v6, 2, v153
	v_lshl_or_b32 v4, v153, 4, v4
	v_readlane_b32 s3, v255, 11
	s_mov_b32 s0, s20
	s_mov_b64 s[8:9], 0
	v_lshl_add_u64 v[4:5], s[2:3], 0, v[4:5]
	v_lshlrev_b32_e32 v144, 2, v6
	s_add_u32 s28, s74, 0x121e0000
	s_addc_u32 s29, s75, 0
	global_load_dwordx4 v[32:35], v144, s[88:89]
	global_load_dwordx4 v[36:39], v144, s[88:89] offset:1024
	global_load_dwordx4 v[40:43], v144, s[88:89] offset:2048
	global_load_dwordx4 v[44:47], v144, s[88:89] offset:3072
.LBB0_16:
	v_lshlrev_b32_e32 v48, 2, v0
	v_add_u32_e32 v49, 0x10000, v48
	v_add_u32_e32 v50, 0x20000, v48
	v_add_u32_e32 v51, 0x30000, v48
	v_add_u32_e32 v52, 0x40000, v48
	v_add_u32_e32 v53, 0x50000, v48
	v_add_u32_e32 v54, 0x60000, v48
	v_add_u32_e32 v55, 0x70000, v48
	v_add_u32_e32 v56, 0x80000, v48
	v_add_u32_e32 v57, 0x90000, v48
	v_add_u32_e32 v58, 0xa0000, v48
	v_add_u32_e32 v59, 0xb0000, v48
	v_add_u32_e32 v60, 0xc0000, v48
	v_add_u32_e32 v61, 0xd0000, v48
	v_add_u32_e32 v62, 0xe0000, v48
	v_add_u32_e32 v63, 0xf0000, v48
	global_load_dword v80, v48, s[28:29]
	global_load_dword v81, v49, s[28:29]
	global_load_dword v82, v50, s[28:29]
	global_load_dword v83, v51, s[28:29]
	global_load_dword v84, v52, s[28:29]
	global_load_dword v85, v53, s[28:29]
	global_load_dword v86, v54, s[28:29]
	global_load_dword v87, v55, s[28:29]
	global_load_dword v88, v56, s[28:29]
	global_load_dword v89, v57, s[28:29]
	global_load_dword v90, v58, s[28:29]
	global_load_dword v91, v59, s[28:29]
	global_load_dword v92, v60, s[28:29]
	global_load_dword v93, v61, s[28:29]
	global_load_dword v94, v62, s[28:29]
	global_load_dword v95, v63, s[28:29]
	global_load_dwordx4 v[64:67], v[4:5], off offset:-3072
	global_load_dwordx4 v[68:71], v[4:5], off offset:-2048
	global_load_dwordx4 v[72:75], v[4:5], off offset:-1024
	global_load_dwordx4 v[76:79], v[4:5], off
	v_add_u32_e32 v0, s0, v0
	v_lshl_add_u64 v[2:3], v[2:3], 0, s[22:23]
	s_waitcnt vmcnt(4)
	v_add_f32_e32 v1, 0, v80
	v_add_f32_e32 v1, v1, v81
	v_add_f32_e32 v1, v1, v82
	v_add_f32_e32 v1, v1, v83
	v_add_f32_e32 v1, v1, v84
	v_add_f32_e32 v1, v1, v85
	v_add_f32_e32 v1, v1, v86
	v_add_f32_e32 v1, v1, v87
	v_add_f32_e32 v1, v1, v88
	v_add_f32_e32 v1, v1, v89
	v_add_f32_e32 v1, v1, v90
	v_add_f32_e32 v1, v1, v91
	v_add_f32_e32 v1, v1, v92
	v_add_f32_e32 v1, v1, v93
	v_add_f32_e32 v1, v1, v94
	v_add_f32_e32 v1, v1, v95
	v_fmamk_f32 v1, v1, 0x3a800000, v192
	v_cmp_gt_f32_e32 vcc, s26, v1
	v_mul_f32_e32 v6, 0x4b800000, v1
	s_nop 0
	v_cndmask_b32_e32 v1, v1, v6, vcc
	v_rsq_f32_e32 v1, v1
	s_nop 0
	v_mul_f32_e32 v6, 0x45800000, v1
	v_cndmask_b32_e32 v6, v1, v6, vcc
	s_nop 1
	v_cmp_lt_i32_e32 vcc, s27, v0
	s_or_b64 s[8:9], vcc, s[8:9]
	s_waitcnt vmcnt(0)
	v_pk_mul_f32 v[64:65], v[64:65], v[6:7] op_sel_hi:[1,0]
	v_pk_mul_f32 v[66:67], v[66:67], v[6:7] op_sel_hi:[1,0]
	v_pk_mul_f32 v[64:65], v[32:33], v[64:65]
	v_pk_mul_f32 v[66:67], v[34:35], v[66:67]
	global_store_dwordx4 v[4:5], v[64:67], off offset:-3072
	v_pk_mul_f32 v[68:69], v[68:69], v[6:7] op_sel_hi:[1,0]
	v_pk_mul_f32 v[70:71], v[70:71], v[6:7] op_sel_hi:[1,0]
	v_pk_mul_f32 v[68:69], v[36:37], v[68:69]
	v_pk_mul_f32 v[70:71], v[38:39], v[70:71]
	global_store_dwordx4 v[4:5], v[68:71], off offset:-2048
	v_pk_mul_f32 v[72:73], v[72:73], v[6:7] op_sel_hi:[1,0]
	v_pk_mul_f32 v[74:75], v[74:75], v[6:7] op_sel_hi:[1,0]
	v_pk_mul_f32 v[72:73], v[40:41], v[72:73]
	v_pk_mul_f32 v[74:75], v[42:43], v[74:75]
	global_store_dwordx4 v[4:5], v[72:75], off offset:-1024
	v_pk_mul_f32 v[76:77], v[76:77], v[6:7] op_sel_hi:[1,0]
	v_pk_mul_f32 v[78:79], v[78:79], v[6:7] op_sel_hi:[1,0]
	v_pk_mul_f32 v[76:77], v[44:45], v[76:77]
	v_pk_mul_f32 v[78:79], v[46:47], v[78:79]
	global_store_dwordx4 v[4:5], v[76:79], off
	v_lshl_add_u64 v[4:5], v[4:5], 0, s[24:25]
	s_andn2_b64 exec, exec, s[8:9]
	s_cbranch_execnz .LBB0_16
